# grid barrier: workgroups poll the top arrival counter against (gen+1)*nx, no separate generation word
# speedup vs baseline: 1.0099x; 1.0052x over previous
; __device__ __forceinline__ unsigned xb_ld(unsigned* p)              { return __hip_atomic_load(p, __ATOMIC_RELAXED, __HIP_MEMORY_SCOPE_AGENT); }
; __device__ __forceinline__ unsigned xb_add(unsigned* p, unsigned v) { return __hip_atomic_fetch_add(p, v, __ATOMIC_RELAXED, __HIP_MEMORY_SCOPE_AGENT); }
; #define XB_SPIN(cond, bar) do { unsigned _sp = 0; while (cond) { __builtin_amdgcn_s_sleep(1); \
;     if ((++_sp & 255u) == 0u) { if (xb_ld(&(bar)[XB_TMO])) break; if (_sp > XB_SPIN_CAP) { atomicAdd(&(bar)[XB_TMO], 1u); break; } } } } while (0)
; __device__ __forceinline__ void xcd_barrier(unsigned* bar, volatile LAS unsigned* st) {
;     ...
;         const unsigned old = xb_add(&bar[XB_XSUB(x)], 1u);
;         const unsigned gen = old / nloc;
;         if (old + 1u == (gen + 1u) * nloc) {
;             __builtin_amdgcn_fence(__ATOMIC_RELEASE, "agent");
;             asm volatile("s_waitcnt vmcnt(0)" ::: "memory");
;             const unsigned og = xb_add(&bar[XB_TOP], 1u);
;             const unsigned tg = og / nx;
;             if (og + 1u == (tg + 1u) * nx) xb_add(&bar[XB_TOPGEN], 1u);
;             else XB_SPIN(xb_ld(&bar[XB_TOPGEN]) == tg, bar);
;             __builtin_amdgcn_fence(__ATOMIC_ACQUIRE, "agent");
;             xb_add(&bar[XB_XGEN(x)], 1u);
;             asm volatile("s_waitcnt vmcnt(0)" ::: "memory");
;         } else {
;             XB_SPIN(xb_ld(&bar[XB_XGEN(x)]) == gen, bar);
.LBB0_872:
	s_or_b64 exec, exec, s[6:7]
	v_cvt_f32_u32_e32 v5, v3
	s_waitcnt vmcnt(0)
	v_readfirstlane_b32 s0, v4
	v_sub_u32_e32 v4, 0, v3
	v_rcp_iflag_f32_e32 v5, v5
	v_add_u32_e32 v6, s0, v1
	v_mul_f32_e32 v5, 0x4f7ffffe, v5
	v_cvt_u32_f32_e32 v5, v5
	v_mul_lo_u32 v1, v4, v5
	v_mul_hi_u32 v1, v5, v1
	v_add_u32_e32 v1, v5, v1
	v_mul_hi_u32 v1, v6, v1
	v_mul_lo_u32 v4, v1, v3
	v_sub_u32_e32 v4, v6, v4
	v_add_u32_e32 v5, 1, v1
	v_cmp_ge_u32_e32 vcc, v4, v3
	s_nop 1
	v_cndmask_b32_e32 v1, v1, v5, vcc
	v_sub_u32_e32 v5, v4, v3
	v_cndmask_b32_e32 v4, v4, v5, vcc
	v_add_u32_e32 v5, 1, v1
	v_cmp_ge_u32_e32 vcc, v4, v3
	v_add_u32_e32 v4, 1, v6
	s_nop 0
	v_cndmask_b32_e32 v1, v1, v5, vcc
	v_mul_lo_u32 v5, v3, v1
	v_add_u32_e32 v3, v5, v3
	v_cmp_ne_u32_e32 vcc, v4, v3
	s_and_saveexec_b64 s[0:1], vcc
	s_xor_b64 s[6:7], exec, s[0:1]
	s_cbranch_execz .LBB0_886
	s_waitcnt lgkmcnt(0)
	v_readlane_b32 s8, v254, 42
	v_readlane_b32 s9, v254, 43
	v_mad_u32_u24 v4, v1, v2, v2
	s_nop 3
	global_load_dword v2, v0, s[8:9] sc1
	s_waitcnt vmcnt(0)
	v_cmp_lt_u32_e32 vcc, v2, v4
	s_and_saveexec_b64 s[0:1], vcc
	s_cbranch_execz .LBB0_885
	s_mov_b32 s20, 1
	s_mov_b64 s[10:11], 0
	s_branch .LBB0_876

; __device__ __forceinline__ unsigned xb_ld(unsigned* p)              { return __hip_atomic_load(p, __ATOMIC_RELAXED, __HIP_MEMORY_SCOPE_AGENT); }
; #define XB_SPIN(cond, bar) do { unsigned _sp = 0; while (cond) { __builtin_amdgcn_s_sleep(1); \
;     if ((++_sp & 255u) == 0u) { if (xb_ld(&(bar)[XB_TMO])) break; if (_sp > XB_SPIN_CAP) { atomicAdd(&(bar)[XB_TMO], 1u); break; } } } } while (0)
; __device__ __forceinline__ void xcd_barrier(unsigned* bar, volatile LAS unsigned* st) {
;     ...
;             XB_SPIN(xb_ld(&bar[XB_XGEN(x)]) == gen, bar);
.LBB0_878:
	global_load_dword v2, v0, s[8:9] sc1
	s_add_i32 s20, s20, 1
	s_mov_b64 s[16:17], -1
	s_waitcnt vmcnt(0)
	v_cmp_ge_u32_e32 vcc, v2, v4
	s_orn2_b64 s[14:15], vcc, exec
	s_branch .LBB0_875

; __device__ __forceinline__ unsigned xb_ld(unsigned* p)              { return __hip_atomic_load(p, __ATOMIC_RELAXED, __HIP_MEMORY_SCOPE_AGENT); }
; __device__ __forceinline__ unsigned xb_add(unsigned* p, unsigned v) { return __hip_atomic_fetch_add(p, v, __ATOMIC_RELAXED, __HIP_MEMORY_SCOPE_AGENT); }
; #define XB_SPIN(cond, bar) do { unsigned _sp = 0; while (cond) { __builtin_amdgcn_s_sleep(1); \
;     if ((++_sp & 255u) == 0u) { if (xb_ld(&(bar)[XB_TMO])) break; if (_sp > XB_SPIN_CAP) { atomicAdd(&(bar)[XB_TMO], 1u); break; } } } } while (0)
; __device__ __forceinline__ void xcd_barrier(unsigned* bar, volatile LAS unsigned* st) {
;     ...
;             const unsigned og = xb_add(&bar[XB_TOP], 1u);
;             const unsigned tg = og / nx;
;             if (og + 1u == (tg + 1u) * nx) xb_add(&bar[XB_TOPGEN], 1u);
;             else XB_SPIN(xb_ld(&bar[XB_TOPGEN]) == tg, bar);
.LBB0_889:
	s_or_b64 exec, exec, s[6:7]
	s_waitcnt vmcnt(0)
	v_readfirstlane_b32 s0, v3
	v_sub_u32_e32 v4, 0, v2
	s_mov_b64 s[6:7], 0
	v_add_u32_e32 v3, s0, v1
	v_cvt_f32_u32_e32 v1, v2
	v_readlane_b32 s0, v254, 44
	v_readlane_b32 s1, v254, 45
	v_rcp_iflag_f32_e32 v1, v1
	s_nop 0
	v_mul_f32_e32 v1, 0x4f7ffffe, v1
	v_cvt_u32_f32_e32 v1, v1
	v_mul_lo_u32 v4, v4, v1
	v_mul_hi_u32 v4, v1, v4
	v_add_u32_e32 v1, v1, v4
	v_mul_hi_u32 v1, v3, v1
	v_mul_lo_u32 v4, v1, v2
	v_sub_u32_e32 v4, v3, v4
	v_cmp_ge_u32_e32 vcc, v4, v2
	v_add_u32_e32 v5, 1, v1
	v_add_u32_e32 v3, 1, v3
	v_cndmask_b32_e32 v1, v1, v5, vcc
	v_sub_u32_e32 v5, v4, v2
	v_cndmask_b32_e32 v4, v4, v5, vcc
	v_cmp_ge_u32_e32 vcc, v4, v2
	v_add_u32_e32 v4, 1, v1
	s_nop 0
	v_cndmask_b32_e32 v1, v1, v4, vcc
	v_mul_lo_u32 v4, v2, v1
	v_add_u32_e32 v6, v4, v2
	v_add_u32_e32 v2, v4, v2
	v_cmp_ne_u32_e32 vcc, v3, v2
	v_mov_b64_e32 v[2:3], s[0:1]
	s_and_saveexec_b64 s[0:1], vcc
	s_cbranch_execz .LBB0_901
	v_readlane_b32 s6, v254, 42
	v_readlane_b32 s7, v254, 43
	s_mov_b64 s[8:9], 0
	s_nop 3
	global_load_dword v2, v0, s[6:7] sc1
	s_waitcnt vmcnt(0)
	v_cmp_lt_u32_e32 vcc, v2, v6
	s_and_saveexec_b64 s[6:7], vcc
	s_cbranch_execz .LBB0_900
	s_mov_b32 s18, 1
	s_branch .LBB0_893

; __device__ __forceinline__ unsigned xb_ld(unsigned* p)              { return __hip_atomic_load(p, __ATOMIC_RELAXED, __HIP_MEMORY_SCOPE_AGENT); }
; #define XB_SPIN(cond, bar) do { unsigned _sp = 0; while (cond) { __builtin_amdgcn_s_sleep(1); \
;     if ((++_sp & 255u) == 0u) { if (xb_ld(&(bar)[XB_TMO])) break; if (_sp > XB_SPIN_CAP) { atomicAdd(&(bar)[XB_TMO], 1u); break; } } } } while (0)
; __device__ __forceinline__ void xcd_barrier(unsigned* bar, volatile LAS unsigned* st) {
;     ...
;             else XB_SPIN(xb_ld(&bar[XB_TOPGEN]) == tg, bar);
.LBB0_895:
	v_readlane_b32 s12, v254, 42
	v_readlane_b32 s13, v254, 43
	s_add_i32 s18, s18, 1
	s_mov_b64 s[14:15], -1
	s_nop 2
	global_load_dword v2, v0, s[12:13] sc1
	s_waitcnt vmcnt(0)
	v_cmp_ge_u32_e32 vcc, v2, v6
	s_orn2_b64 s[12:13], vcc, exec
	s_branch .LBB0_892
